# attention: first two K/V tiles loaded together; gate loads issued before the last softmax segment
# baseline (speedup 1.0000x reference)
; __device__ __forceinline__ unsigned cvtpk(float lo, float hi) { f32x2 v = {lo, hi}; bf16x2_t b = __builtin_convertvector(v, bf16x2_t); return *(unsigned*)&b; }
; __device__ __forceinline__ float lo16(unsigned w) { return __uint_as_float(w << 16); }
; __device__ __forceinline__ float hi16(unsigned w) { return __uint_as_float(w & 0xffff0000u); }
; #define SWAIT() asm volatile("s_waitcnt vmcnt(3)" ::: "memory")
; __device__ void phase_attn(const Params& p, char* lds) {
;     ...
;   for (int it = slot; it < nitems / 8; it += per) {
;     const int pair = (it >> 5) * 8 + xcd, qblk = it & 31;
;     const int b = pair >> 4, h = pair & 15;
;     const size_t row0 = (size_t)b * TL;
;     const size_t qrow = row0 + qblk * 256 + wid * 32 + r32;
;     const bf16_t* Kh = KVg + row0 * 2048 + h * 128;
;     const bf16_t* Kp = KPg + row0 * 32;
;     float m_reg = 0.f, l_reg = 0.f;
;     f32x16 o[2];
; #pragma unroll
;     for (int dd = 0; dd < 2; ++dd)
; #pragma unroll
;       for (int r = 0; r < 16; ++r) o[dd][r] = 0.f;
;     bf16x8 qr[6];
;     {
;       const bf16_t* Qw = Qg + qrow * 1536 + h * 96 + hi * 8;
; #pragma unroll
;       for (int d0 = 0; d0 < 6; ++d0) qr[d0] = *(const bf16x8*)(Qw + d0 * 16);
;       const int t = qblk * 256 + wid * 32 + r32;
;       const f32x2* tb = rope + (hi ? (t & 63) : (t >> 6)) * 8;
;       const u32x4 x1 = *(const u32x4*)&qr[4], x2 = *(const u32x4*)&qr[5];
;       u32x4 n1, n2;
; #pragma unroll
;       for (int q = 0; q < 4; ++q) {
;         const f32x2 csA = tb[2 * q], csB = tb[2 * q + 1];
;         const float a0 = lo16(x1[q]), a1 = hi16(x1[q]), b0 = lo16(x2[q]), b1 = hi16(x2[q]);
;         n1[q] = cvtpk(a0 * csA[0] - b0 * csA[1], a1 * csB[0] - b1 * csB[1]);
;         n2[q] = cvtpk(a0 * csA[1] + b0 * csA[0], a1 * csB[1] + b1 * csB[0]);
;       }
;       qr[4] = *(bf16x8*)&n1; qr[5] = *(bf16x8*)&n2;
;     }
;     struct { bf16x8 vs, ks, ps; } sr_[2];
;     ...
;     f32x16 pA0, pA1, pB0, pB1; float alA, alB; bf16x8 pa0, pa1, pa2, pa3;
;     constexpr int NT = TL / 64;
;     SLOAD(0, 0); asm volatile("s_waitcnt vmcnt(0)" ::: "memory"); SWRITE(0, 0); __syncthreads();
;     at_qkt(pA0, pA1, K_lds, qr, r32, hi, 0.f); at_partialSM(pA0, pA1, m_reg, alA, true);
;     SLOAD(1, 64); SLOAD(0, 128);
;     SWAIT(); SWRITE(1, 1); __syncthreads();
.Lat_item:
	s_lshr_b32 s16, s12, 5
	s_lshl_b32 s16, s16, 3
	s_add_i32 s16, s16, s43
	s_and_b32 s20, s12, 31
	s_lshr_b32 s22, s16, 4
	s_and_b32 s21, s16, 15
	s_mul_i32 s17, s22, 0x2100000
	s_lshl_b32 s18, s21, 8
	s_add_i32 s17, s17, s18
	s_add_u32 s17, s17, 0x29400000
	s_add_u32 s4, s86, s17
	s_addc_u32 s5, s87, 0
	s_mul_i32 s17, s22, 0x84000
	s_add_u32 s17, s17, 0x1de80000
	s_add_u32 s6, s86, s17
	s_addc_u32 s7, s87, 0
	s_mul_i32 s17, s22, 0x2100
	s_lshl_b32 s18, s20, 8
	s_add_i32 s17, s17, s18
	s_mul_i32 s18, s17, 0xc00
	s_mul_i32 s19, s21, 0xc0
	s_add_i32 s18, s18, s19
	s_add_u32 s18, s18, 0x8400000
	s_add_u32 s10, s86, s18
	s_addc_u32 s11, s87, 0
	s_lshl_b32 s18, s17, 11
	s_lshl_b32 s19, s21, 7
	s_add_i32 s18, s18, s19
	s_add_u32 s18, s18, 0x21000000
	s_add_u32 s28, s86, s18
	s_addc_u32 s29, s87, 0
	global_load_dwordx4 v[80:83], v234, s[10:11] offset:0
	global_load_dwordx4 v[84:87], v234, s[10:11] offset:32
	global_load_dwordx4 v[88:91], v234, s[10:11] offset:64
	global_load_dwordx4 v[92:95], v234, s[10:11] offset:96
	global_load_dwordx4 v[96:99], v234, s[10:11] offset:128
	global_load_dwordx4 v[100:103], v234, s[10:11] offset:160
	s_and_b32 s16, s14, 1
	s_lshl_b32 s16, s16, 5
	v_and_b32_e32 v183, 31, v178
	v_add_u32_e32 v183, s16, v183
	v_lshlrev_b32_e32 v183, 6, v183
	s_lshl_b32 s16, s20, 2
	s_lshr_b32 s17, s14, 1
	s_add_i32 s16, s16, s17
	s_lshl_b32 s16, s16, 6
	v_mov_b32_e32 v228, s16
	v_and_b32_e32 v229, 32, v178
	v_cmp_ne_u32_e32 vcc, 0, v229
	s_nop 1
	v_cndmask_b32_e32 v183, v228, v183, vcc
	global_load_dwordx4 v[32:35], v183, s[34:35] offset:0
	global_load_dwordx4 v[36:39], v183, s[34:35] offset:16
	global_load_dwordx4 v[40:43], v183, s[34:35] offset:32
	global_load_dwordx4 v[44:47], v183, s[34:35] offset:48
	s_barrier
	global_load_dwordx4 v[120:123], v129, s[4:5]
	global_load_dwordx4 v[124:127], v129, s[4:5] offset:128
	global_load_dwordx4 v[132:135], v130, s[6:7]
	s_add_u32 s4, s4, 0x40000
	s_addc_u32 s5, s5, 0
	s_add_u32 s6, s6, 0x1000
	s_addc_u32 s7, s7, 0
	global_load_dwordx4 v[136:139], v129, s[4:5]
	global_load_dwordx4 v[140:143], v129, s[4:5] offset:128
	global_load_dwordx4 v[144:147], v130, s[6:7]
	s_add_u32 s4, s4, 0x40000
	s_addc_u32 s5, s5, 0
	s_add_u32 s6, s6, 0x1000
	s_addc_u32 s7, s7, 0
	s_waitcnt vmcnt(0)
	ds_write_b128 v167, v[120:123] offset:0
	ds_write_b128 v131, v[124:127] offset:0
	ds_write_b128 v169, v[132:135] offset:0
	ds_write_b128 v167, v[136:139] offset:13312
	ds_write_b128 v131, v[140:143] offset:16384
	ds_write_b128 v169, v[144:147] offset:13312
	s_waitcnt lgkmcnt(0)
	global_load_dwordx4 v[120:123], v129, s[4:5]
	global_load_dwordx4 v[124:127], v129, s[4:5] offset:128
	global_load_dwordx4 v[132:135], v130, s[6:7]
	s_add_u32 s4, s4, 0x40000
	s_addc_u32 s5, s5, 0
	s_add_u32 s6, s6, 0x1000
	s_addc_u32 s7, s7, 0
	v_lshlrev_b32_e32 v175, 16, v96
	v_and_b32_e32 v183, 0xffff0000, v96
	v_lshlrev_b32_e32 v228, 16, v100
	v_and_b32_e32 v229, 0xffff0000, v100
	v_mul_f32_e32 v230, v228, v33
	v_mul_f32_e32 v174, v229, v35
	v_fma_f32 v230, v175, v32, -v230
	v_fma_f32 v174, v183, v34, -v174
	v_mul_f32_e32 v175, v175, v33
	v_mul_f32_e32 v183, v183, v35
	v_fma_f32 v175, v228, v32, v175
	v_fma_f32 v183, v229, v34, v183
	v_cvt_pk_bf16_f32 v96, v230, v174
	v_cvt_pk_bf16_f32 v100, v175, v183
	v_lshlrev_b32_e32 v175, 16, v97
	v_and_b32_e32 v183, 0xffff0000, v97
	v_lshlrev_b32_e32 v228, 16, v101
	v_and_b32_e32 v229, 0xffff0000, v101
	v_mul_f32_e32 v230, v228, v37
	v_mul_f32_e32 v174, v229, v39
	v_fma_f32 v230, v175, v36, -v230
	v_fma_f32 v174, v183, v38, -v174
	v_mul_f32_e32 v175, v175, v37
	v_mul_f32_e32 v183, v183, v39
	v_fma_f32 v175, v228, v36, v175
	v_fma_f32 v183, v229, v38, v183
	v_cvt_pk_bf16_f32 v97, v230, v174
	v_cvt_pk_bf16_f32 v101, v175, v183
	v_lshlrev_b32_e32 v175, 16, v98
	v_and_b32_e32 v183, 0xffff0000, v98
	v_lshlrev_b32_e32 v228, 16, v102
	v_and_b32_e32 v229, 0xffff0000, v102
	v_mul_f32_e32 v230, v228, v41
	v_mul_f32_e32 v174, v229, v43
	v_fma_f32 v230, v175, v40, -v230
	v_fma_f32 v174, v183, v42, -v174
	v_mul_f32_e32 v175, v175, v41
	v_mul_f32_e32 v183, v183, v43
	v_fma_f32 v175, v228, v40, v175
	v_fma_f32 v183, v229, v42, v183
	v_cvt_pk_bf16_f32 v98, v230, v174
	v_cvt_pk_bf16_f32 v102, v175, v183
	v_lshlrev_b32_e32 v175, 16, v99
	v_and_b32_e32 v183, 0xffff0000, v99
	v_lshlrev_b32_e32 v228, 16, v103
	v_and_b32_e32 v229, 0xffff0000, v103
	v_mul_f32_e32 v230, v228, v45
	v_mul_f32_e32 v174, v229, v47
	v_fma_f32 v230, v175, v44, -v230
	v_fma_f32 v174, v183, v46, -v174
	v_mul_f32_e32 v175, v175, v45
	v_mul_f32_e32 v183, v183, v47
	v_fma_f32 v175, v228, v44, v175
	v_fma_f32 v183, v229, v46, v183
	v_cvt_pk_bf16_f32 v99, v230, v174
	v_cvt_pk_bf16_f32 v103, v175, v183
	v_mov_b32_e32 v0, 0
	v_mov_b32_e32 v1, 0
	v_mov_b32_e32 v2, 0
	v_mov_b32_e32 v3, 0
	v_mov_b32_e32 v4, 0
	v_mov_b32_e32 v5, 0
	v_mov_b32_e32 v6, 0
	v_mov_b32_e32 v7, 0
	v_mov_b32_e32 v8, 0
	v_mov_b32_e32 v9, 0
	v_mov_b32_e32 v10, 0
	v_mov_b32_e32 v11, 0
	v_mov_b32_e32 v12, 0
	v_mov_b32_e32 v13, 0
	v_mov_b32_e32 v14, 0
	v_mov_b32_e32 v15, 0
	v_mov_b32_e32 v16, 0
	v_mov_b32_e32 v17, 0
	v_mov_b32_e32 v18, 0
	v_mov_b32_e32 v19, 0
	v_mov_b32_e32 v20, 0
	v_mov_b32_e32 v21, 0
	v_mov_b32_e32 v22, 0
	v_mov_b32_e32 v23, 0
	v_mov_b32_e32 v24, 0
	v_mov_b32_e32 v25, 0
	v_mov_b32_e32 v26, 0
	v_mov_b32_e32 v27, 0
	v_mov_b32_e32 v28, 0
	v_mov_b32_e32 v29, 0
	v_mov_b32_e32 v30, 0
	v_mov_b32_e32 v31, 0
	v_mov_b32_e32 v173, 0
	s_barrier
	ds_read_b128 v[184:187], v170 offset:0
	ds_read_b128 v[188:191], v170 offset:6656
	ds_read_b128 v[192:195], v170 offset:32
	ds_read_b128 v[196:199], v170 offset:6688
	s_cmp_eq_u32 s15, 0
	s_cbranch_scc1 .Lat_nostag
	s_barrier

; __device__ __forceinline__ void at_finishSM(f32x16& p0, f32x16& p1, float alpha, float& l_reg, bf16x8& pa0, bf16x8& pa1, bf16x8& pa2, bf16x8& pa3) {
; #pragma unroll
;   for (int r = 0; r < 16; ++r) p1[r] = __builtin_amdgcn_exp2f(p1[r]);
;   float ps = 0;
; #pragma unroll
;   for (int r = 0; r < 16; ++r) ps += p0[r];
; #pragma unroll
;   for (int r = 0; r < 16; ++r) ps += p1[r];
;   { auto rr = __builtin_amdgcn_permlane32_swap(__float_as_uint(ps), __float_as_uint(ps), false, false);
;     ps = __uint_as_float(rr[0]) + __uint_as_float(rr[1]); }
;   l_reg = l_reg * alpha + ps;
;     ...
;   PK4(p0, 0, pa0); PK4(p0, 8, pa1); PK4(p1, 0, pa2); PK4(p1, 8, pa3);
;     ...
; }
; __device__ __forceinline__ void at_qkt(f32x16& p0, f32x16& p1, const char* Ks, const bf16x8* qr, int r32, int hi, float negm) {
; #pragma unroll
;   for (int r = 0; r < 16; ++r) { p0[r] = negm; p1[r] = negm; }
; #pragma unroll
;   for (int d0 = 0; d0 < 6; ++d0) {
;     const bf16x8 b0 = *(const bf16x8*)(Ks + r32 * AT_KROW + d0 * 32 + hi * 16);
;     const bf16x8 b1 = *(const bf16x8*)(Ks + (32 + r32) * AT_KROW + d0 * 32 + hi * 16);
;     p0 = MFMA(b0, qr[d0], p0);
;     p1 = MFMA(b1, qr[d0], p1);
;   }
; }
; __device__ __forceinline__ int v_st(int k, int c) { const int kk = (k & ~0xC) | ((k & 4) << 1) | ((k & 8) >> 1); return ((kk >> 3) * 4 + (c >> 5)) * 512 + ((kk & 7) * 32 + (c & 31)) * 2; }
; __device__ __forceinline__ int v_rd_base(int lane) { return ((lane & 3) << 3) | (((lane >> 2) & 3) << 6) | (((lane >> 4) & 1) << 5) | (((lane >> 5) & 1) << 8); }
; template <int OFF> __device__ __forceinline__ s16x4 tr_read(int vb) {
;   s16x4 r; asm volatile("ds_read_b64_tr_b16 %0, %1 offset:%2" : "=&v"(r) : "v"(vb), "i"(OFF) : "memory"); return r;
; }
; template <int D0> __device__ __forceinline__ void pv_one(f32x16& od, int vb, bf16x8 pa0, bf16x8 pa1, bf16x8 pa2, bf16x8 pa3) {
;   const s16x4 l0 = tr_read<v_rd_off(D0, 0, 0)>(vb), h0 = tr_read<v_rd_off(D0, 0, 1)>(vb), l1 = tr_read<v_rd_off(D0, 1, 0)>(vb), h1 = tr_read<v_rd_off(D0, 1, 1)>(vb);
;   const s16x4 l2 = tr_read<v_rd_off(D0, 2, 0)>(vb), h2 = tr_read<v_rd_off(D0, 2, 1)>(vb), l3 = tr_read<v_rd_off(D0, 3, 0)>(vb), h3 = tr_read<v_rd_off(D0, 3, 1)>(vb);
;   asm volatile("s_waitcnt lgkmcnt(0)" ::: "memory"); SBAR();
;     ...
;   od = MFMA(pa0, PK(l0, h0), od);
;   od = MFMA(pa1, PK(l1, h1), od);
;   od = MFMA(pa2, PK(l2, h2), od);
;   od = MFMA(pa3, PK(l3, h3), od);
;     ...
; }
.Lat_rare_t130_back:
	v_add_f32_e32 v173, v173, v175
	v_cvt_pk_bf16_f32 v104, v32, v33
	v_cvt_pk_bf16_f32 v105, v34, v35
	v_cvt_pk_bf16_f32 v106, v36, v37
	v_cvt_pk_bf16_f32 v107, v38, v39
	v_cvt_pk_bf16_f32 v108, v40, v41
	v_cvt_pk_bf16_f32 v109, v42, v43
	v_cvt_pk_bf16_f32 v110, v44, v45
	v_cvt_pk_bf16_f32 v111, v46, v47
	v_cvt_pk_bf16_f32 v112, v48, v49
	v_cvt_pk_bf16_f32 v113, v50, v51
	v_cvt_pk_bf16_f32 v114, v52, v53
	v_cvt_pk_bf16_f32 v115, v54, v55
	v_cvt_pk_bf16_f32 v116, v56, v57
	v_cvt_pk_bf16_f32 v117, v58, v59
	v_cvt_pk_bf16_f32 v118, v60, v61
	v_cvt_pk_bf16_f32 v119, v62, v63
	ds_read_b128 v[184:187], v170 offset:39936
	ds_read_b128 v[188:191], v170 offset:46592
	ds_read_b128 v[192:195], v170 offset:39968
	ds_read_b128 v[196:199], v170 offset:46624
	s_barrier
	ds_read_b128 v[200:203], v170 offset:40000
	ds_read_b128 v[204:207], v170 offset:46656
	s_waitcnt lgkmcnt(4)
	v_mfma_f32_32x32x16_bf16 v[32:47], v[184:187], v[80:83], v[64:79]
	v_mfma_f32_32x32x16_bf16 v[48:63], v[188:191], v[80:83], v[64:79]
	ds_read_b128 v[208:211], v170 offset:40032
	ds_read_b128 v[212:215], v170 offset:46688
	s_waitcnt lgkmcnt(4)
	v_mfma_f32_32x32x16_bf16 v[32:47], v[192:195], v[84:87], v[32:47]
	v_mfma_f32_32x32x16_bf16 v[48:63], v[196:199], v[84:87], v[48:63]
	ds_read_b128 v[184:187], v170 offset:40064
	ds_read_b128 v[188:191], v170 offset:46720
	s_waitcnt lgkmcnt(4)
	v_mfma_f32_32x32x16_bf16 v[32:47], v[200:203], v[88:91], v[32:47]
	v_mfma_f32_32x32x16_bf16 v[48:63], v[204:207], v[88:91], v[48:63]
	ds_read_b128 v[192:195], v170 offset:40096
	ds_read_b128 v[196:199], v170 offset:46752
	s_waitcnt lgkmcnt(4)
	v_mfma_f32_32x32x16_bf16 v[32:47], v[208:211], v[92:95], v[32:47]
	v_mfma_f32_32x32x16_bf16 v[48:63], v[212:215], v[92:95], v[48:63]
	ds_read_b64_tr_b16 v[148:149], v171 offset:32768
	ds_read_b64_tr_b16 v[150:151], v171 offset:34816
	ds_read_b64_tr_b16 v[152:153], v171 offset:36864
	ds_read_b64_tr_b16 v[154:155], v171 offset:38912
	s_waitcnt lgkmcnt(6)
	v_mfma_f32_32x32x16_bf16 v[32:47], v[184:187], v[96:99], v[32:47]
	v_mfma_f32_32x32x16_bf16 v[48:63], v[188:191], v[96:99], v[48:63]
	ds_read_b64_tr_b16 v[156:157], v171 offset:40960
	ds_read_b64_tr_b16 v[158:159], v171 offset:43008
	ds_read_b64_tr_b16 v[216:217], v171 offset:45056
	ds_read_b64_tr_b16 v[218:219], v171 offset:47104
	s_waitcnt lgkmcnt(8)
	v_mfma_f32_32x32x16_bf16 v[32:47], v[192:195], v[100:103], v[32:47]
	v_mfma_f32_32x32x16_bf16 v[48:63], v[196:199], v[100:103], v[48:63]
	ds_read_b64_tr_b16 v[220:221], v171 offset:33280
	ds_read_b64_tr_b16 v[222:223], v171 offset:35328
	ds_read_b64_tr_b16 v[224:225], v171 offset:37376
	ds_read_b64_tr_b16 v[226:227], v171 offset:39424
	s_waitcnt lgkmcnt(10)
	v_mfma_f32_32x32x16_bf16 v[0:15], v[104:107], v[148:151], v[0:15]
	s_waitcnt lgkmcnt(8)
	v_mfma_f32_32x32x16_bf16 v[0:15], v[108:111], v[152:155], v[0:15]
	ds_read_b64_tr_b16 v[236:237], v171 offset:41472
	ds_read_b64_tr_b16 v[238:239], v171 offset:43520
	ds_read_b64_tr_b16 v[240:241], v171 offset:45568
	ds_read_b64_tr_b16 v[242:243], v171 offset:47616
	s_waitcnt lgkmcnt(10)
	v_mfma_f32_32x32x16_bf16 v[0:15], v[112:115], v[156:159], v[0:15]
	s_waitcnt lgkmcnt(8)
	v_mfma_f32_32x32x16_bf16 v[0:15], v[116:119], v[216:219], v[0:15]
	s_waitcnt lgkmcnt(6)
	v_mfma_f32_32x32x16_bf16 v[16:31], v[104:107], v[220:223], v[16:31]
	s_waitcnt lgkmcnt(4)
	v_mfma_f32_32x32x16_bf16 v[16:31], v[108:111], v[224:227], v[16:31]
	s_waitcnt lgkmcnt(2)
	v_mfma_f32_32x32x16_bf16 v[16:31], v[112:115], v[236:239], v[16:31]
	s_waitcnt lgkmcnt(0)
	v_mfma_f32_32x32x16_bf16 v[16:31], v[116:119], v[240:243], v[16:31]
	s_barrier
; __device__ __forceinline__ int crow(int r, int hi) { return (r & 3) + 8 * (r >> 2) + 4 * hi; }
; #define SBAR() __builtin_amdgcn_sched_barrier(0)
; #define RESC(a) do { if (__any((a) < 1.f)) { if (hi == 0) al_l[r32] = (a); asm volatile("s_waitcnt lgkmcnt(0)" ::: "memory"); \
;     _Pragma("unroll") for (int dd = 0; dd < 2; ++dd) _Pragma("unroll") for (int r = 0; r < 16; ++r) o[dd][r] *= al_l[crow(r, hi)]; } } while (0)
; __device__ void phase_attn(const Params& p, char* lds) {
;     ...
;     SBAR(); at_qkt(pB0, pB1, K_lds + AT_SHMK, qr, r32, hi, -m_reg);
;     at_finishSM(pA0, pA1, alA, l_reg, pa0, pa1, pa2, pa3); SBAR();
;     pv_d0(o, vb0, pa0, pa1, pa2, pa3); at_partialSM(pB0, pB1, m_reg, alB, false);
;     __syncthreads(); RESC(alB);
;     at_finishSM(pB0, pB1, alB, l_reg, pa0, pa1, pa2, pa3); SBAR();
;     pv_d0(o, vb0 + AT_SHMV, pa0, pa1, pa2, pa3);
;     ...
;     bf16_t gin[32];
; #pragma unroll
;     for (int r = 0; r < 16; ++r) { gin[2 * r] = Gw[(size_t)crow(r, hi) * 1024]; gin[2 * r + 1] = Gw[(size_t)crow(r, hi) * 1024 + 32]; }
;     asm volatile("" ::: "memory");
	s_add_u32 s8, s28, 0x0
	s_addc_u32 s9, s29, 0
	global_load_ushort v120, v235, s[8:9] offset:0
	global_load_ushort v121, v235, s[8:9] offset:64
	global_load_ushort v122, v235, s[8:9] offset:2048
	global_load_ushort v123, v235, s[8:9] offset:2112
	s_add_u32 s8, s28, 0x1000
	s_addc_u32 s9, s29, 0
	global_load_ushort v124, v235, s[8:9] offset:0
	global_load_ushort v125, v235, s[8:9] offset:64
	global_load_ushort v126, v235, s[8:9] offset:2048
	global_load_ushort v127, v235, s[8:9] offset:2112
	s_add_u32 s8, s28, 0x4000
	s_addc_u32 s9, s29, 0
	global_load_ushort v132, v235, s[8:9] offset:0
	global_load_ushort v133, v235, s[8:9] offset:64
	global_load_ushort v134, v235, s[8:9] offset:2048
	global_load_ushort v135, v235, s[8:9] offset:2112
	s_add_u32 s8, s28, 0x5000
	s_addc_u32 s9, s29, 0
	global_load_ushort v136, v235, s[8:9] offset:0
	global_load_ushort v137, v235, s[8:9] offset:64
	global_load_ushort v138, v235, s[8:9] offset:2048
	global_load_ushort v139, v235, s[8:9] offset:2112
	s_add_u32 s8, s28, 0x8000
	s_addc_u32 s9, s29, 0
	global_load_ushort v140, v235, s[8:9] offset:0
	global_load_ushort v141, v235, s[8:9] offset:64
	global_load_ushort v142, v235, s[8:9] offset:2048
	global_load_ushort v143, v235, s[8:9] offset:2112
	s_add_u32 s8, s28, 0x9000
	s_addc_u32 s9, s29, 0
	global_load_ushort v144, v235, s[8:9] offset:0
	global_load_ushort v145, v235, s[8:9] offset:64
	global_load_ushort v146, v235, s[8:9] offset:2048
	global_load_ushort v147, v235, s[8:9] offset:2112
	s_add_u32 s8, s28, 0xc000
	s_addc_u32 s9, s29, 0
	global_load_ushort v200, v235, s[8:9] offset:0
	global_load_ushort v201, v235, s[8:9] offset:64
	global_load_ushort v202, v235, s[8:9] offset:2048
	global_load_ushort v203, v235, s[8:9] offset:2112
	s_add_u32 s8, s28, 0xd000
	s_addc_u32 s9, s29, 0
	global_load_ushort v204, v235, s[8:9] offset:0
	global_load_ushort v205, v235, s[8:9] offset:64
	global_load_ushort v206, v235, s[8:9] offset:2048
	global_load_ushort v207, v235, s[8:9] offset:2112
	v_exp_f32_e32 v32, v32
	v_exp_f32_e32 v48, v48
	v_exp_f32_e32 v33, v33
	v_exp_f32_e32 v49, v49
	v_exp_f32_e32 v34, v34
	v_exp_f32_e32 v50, v50
	v_exp_f32_e32 v35, v35
	v_exp_f32_e32 v51, v51
	v_exp_f32_e32 v36, v36
	v_exp_f32_e32 v52, v52
	v_exp_f32_e32 v37, v37
	v_exp_f32_e32 v53, v53
	v_exp_f32_e32 v38, v38
	v_exp_f32_e32 v54, v54
	v_exp_f32_e32 v39, v39
	v_exp_f32_e32 v55, v55
	v_exp_f32_e32 v40, v40
	v_exp_f32_e32 v56, v56
	v_exp_f32_e32 v41, v41
	v_exp_f32_e32 v57, v57
	v_exp_f32_e32 v42, v42
	v_exp_f32_e32 v58, v58
	v_exp_f32_e32 v43, v43
	v_exp_f32_e32 v59, v59
	v_exp_f32_e32 v44, v44
	v_exp_f32_e32 v60, v60
	v_exp_f32_e32 v45, v45
	v_exp_f32_e32 v61, v61
	v_exp_f32_e32 v46, v46
	v_exp_f32_e32 v62, v62
	v_exp_f32_e32 v47, v47
	v_exp_f32_e32 v63, v63
	v_add_f32_e32 v175, v32, v33
	v_add_f32_e32 v174, v48, v49
	v_add_f32_e32 v175, v175, v34
	v_add_f32_e32 v174, v174, v50
	v_add_f32_e32 v175, v175, v35
	v_add_f32_e32 v174, v174, v51
	v_add_f32_e32 v175, v175, v36
	v_add_f32_e32 v174, v174, v52
	v_add_f32_e32 v175, v175, v37
	v_add_f32_e32 v174, v174, v53
	v_add_f32_e32 v175, v175, v38
	v_add_f32_e32 v174, v174, v54
	v_add_f32_e32 v175, v175, v39
	v_add_f32_e32 v174, v174, v55
	v_add_f32_e32 v175, v175, v40
	v_add_f32_e32 v174, v174, v56
	v_add_f32_e32 v175, v175, v41
	v_add_f32_e32 v174, v174, v57
	v_add_f32_e32 v175, v175, v42
	v_add_f32_e32 v174, v174, v58
	v_add_f32_e32 v175, v175, v43
	v_add_f32_e32 v174, v174, v59
	v_add_f32_e32 v175, v175, v44
	v_add_f32_e32 v174, v174, v60
	v_add_f32_e32 v175, v175, v45
	v_add_f32_e32 v174, v174, v61
	v_add_f32_e32 v175, v175, v46
	v_add_f32_e32 v174, v174, v62
	v_add_f32_e32 v175, v175, v47
	v_add_f32_e32 v174, v174, v63
	v_add_f32_e32 v175, v175, v174
	v_cmp_ge_f32_e32 vcc, s23, v175
	s_cmp_eq_u64 vcc, exec
	s_cbranch_scc0 .Lat_rare_t131

; __device__ __forceinline__ float bf2f(bf16_t u) { return __uint_as_float(((unsigned)u) << 16); }
; __device__ __forceinline__ bf16_t f2bf(float f) { return (bf16_t)(cvtpk(f, 0.f) & 0xffffu); }
; __device__ __forceinline__ int crow(int r, int hi) { return (r & 3) + 8 * (r >> 2) + 4 * hi; }
; __device__ __forceinline__ float sigmoidf_(float x) { return __builtin_amdgcn_rcpf(1.f + __expf(-x)); }
; __device__ void phase_attn(const Params& p, char* lds) {
;     ...
;     if (hi == 0) li_l[r32] = l_reg;
;     asm volatile("s_waitcnt lgkmcnt(0)" ::: "memory");
;     float rli[16];
; #pragma unroll
;     for (int r = 0; r < 16; ++r) rli[r] = __builtin_amdgcn_rcpf(li_l[crow(r, hi)]);
;     bf16_t* Gw = G1 + (row0 + qblk * 256 + wid * 32) * 1024 + h * 64 + r32;
;     bf16_t gin[32];
; #pragma unroll
;     for (int r = 0; r < 16; ++r) { gin[2 * r] = Gw[(size_t)crow(r, hi) * 1024]; gin[2 * r + 1] = Gw[(size_t)crow(r, hi) * 1024 + 32]; }
;     asm volatile("" ::: "memory");
; #pragma unroll
;     for (int r = 0; r < 16; ++r) {
;       const int orow = crow(r, hi);
; #pragma unroll
;       for (int d0 = 0; d0 < 2; ++d0) {
;         const float gt = bf2f(gin[2 * r + d0]);
;         Gw[(size_t)orow * 1024 + d0 * 32] = f2bf(o[d0][r] * rli[r] * gt * sigmoidf_(gt));
;       }
;     }
.Lat_nobal:
	v_mov_b32_e32 v175, v173
	s_nop 1
	v_permlane32_swap_b32_e32 v173, v175
	v_add_f32_e32 v173, v173, v175
	ds_write_b32 v244, v173 offset:128
	s_waitcnt lgkmcnt(0)
	ds_read_b128 v[184:187], v245 offset:128
	ds_read_b128 v[188:191], v245 offset:160
	ds_read_b128 v[192:195], v245 offset:192
	ds_read_b128 v[196:199], v245 offset:224
	s_waitcnt lgkmcnt(0)
	v_rcp_f32_e32 v184, v184
	v_rcp_f32_e32 v185, v185
	v_rcp_f32_e32 v186, v186
	v_rcp_f32_e32 v187, v187
	v_rcp_f32_e32 v188, v188
	v_rcp_f32_e32 v189, v189
	v_rcp_f32_e32 v190, v190
	v_rcp_f32_e32 v191, v191
	v_rcp_f32_e32 v192, v192
	v_rcp_f32_e32 v193, v193
	v_rcp_f32_e32 v194, v194
	v_rcp_f32_e32 v195, v195
	v_rcp_f32_e32 v196, v196
	v_rcp_f32_e32 v197, v197
	v_rcp_f32_e32 v198, v198
	v_rcp_f32_e32 v199, v199
	v_mul_f32_e32 v0, v0, v184
	v_mul_f32_e32 v16, v16, v184
	v_mul_f32_e32 v1, v1, v185
	v_mul_f32_e32 v17, v17, v185
	v_mul_f32_e32 v2, v2, v186
	v_mul_f32_e32 v18, v18, v186
	v_mul_f32_e32 v3, v3, v187
	v_mul_f32_e32 v19, v19, v187
	v_mul_f32_e32 v4, v4, v188
	v_mul_f32_e32 v20, v20, v188
	v_mul_f32_e32 v5, v5, v189
	v_mul_f32_e32 v21, v21, v189
	v_mul_f32_e32 v6, v6, v190
	v_mul_f32_e32 v22, v22, v190
	v_mul_f32_e32 v7, v7, v191
	v_mul_f32_e32 v23, v23, v191
	v_mul_f32_e32 v8, v8, v192
	v_mul_f32_e32 v24, v24, v192
	v_mul_f32_e32 v9, v9, v193
	v_mul_f32_e32 v25, v25, v193
	v_mul_f32_e32 v10, v10, v194
	v_mul_f32_e32 v26, v26, v194
	v_mul_f32_e32 v11, v11, v195
	v_mul_f32_e32 v27, v27, v195
	v_mul_f32_e32 v12, v12, v196
	v_mul_f32_e32 v28, v28, v196
	v_mul_f32_e32 v13, v13, v197
	v_mul_f32_e32 v29, v29, v197
	v_mul_f32_e32 v14, v14, v198
	v_mul_f32_e32 v30, v30, v198
	v_mul_f32_e32 v15, v15, v199
	v_mul_f32_e32 v31, v31, v199
	s_waitcnt vmcnt(0)
	v_lshlrev_b32_e32 v32, 16, v120
	v_lshlrev_b32_e32 v33, 16, v121
	v_lshlrev_b32_e32 v34, 16, v122
	v_lshlrev_b32_e32 v35, 16, v123
	v_lshlrev_b32_e32 v36, 16, v124
	v_lshlrev_b32_e32 v37, 16, v125
	v_lshlrev_b32_e32 v38, 16, v126
	v_lshlrev_b32_e32 v39, 16, v127
	v_mul_f32_e32 v64, 0xbfb8aa3b, v32
	v_mul_f32_e32 v65, 0xbfb8aa3b, v33
	v_mul_f32_e32 v66, 0xbfb8aa3b, v34
	v_mul_f32_e32 v67, 0xbfb8aa3b, v35
	v_mul_f32_e32 v68, 0xbfb8aa3b, v36
	v_mul_f32_e32 v69, 0xbfb8aa3b, v37
	v_mul_f32_e32 v70, 0xbfb8aa3b, v38
	v_mul_f32_e32 v71, 0xbfb8aa3b, v39
	v_exp_f32_e32 v64, v64
	v_exp_f32_e32 v65, v65
	v_exp_f32_e32 v66, v66
	v_exp_f32_e32 v67, v67
	v_exp_f32_e32 v68, v68
	v_exp_f32_e32 v69, v69
	v_exp_f32_e32 v70, v70
	v_exp_f32_e32 v71, v71
	v_add_f32_e32 v64, 1.0, v64
	v_add_f32_e32 v65, 1.0, v65
	v_add_f32_e32 v66, 1.0, v66
	v_add_f32_e32 v67, 1.0, v67
	v_add_f32_e32 v68, 1.0, v68
	v_add_f32_e32 v69, 1.0, v69
	v_add_f32_e32 v70, 1.0, v70
	v_add_f32_e32 v71, 1.0, v71
	v_rcp_f32_e32 v64, v64
	v_rcp_f32_e32 v65, v65
	v_rcp_f32_e32 v66, v66
	v_rcp_f32_e32 v67, v67
	v_rcp_f32_e32 v68, v68
	v_rcp_f32_e32 v69, v69
	v_rcp_f32_e32 v70, v70
	v_rcp_f32_e32 v71, v71
	v_mul_f32_e32 v0, v0, v32
	v_mul_f32_e32 v16, v16, v33
	v_mul_f32_e32 v1, v1, v34
	v_mul_f32_e32 v17, v17, v35
	v_mul_f32_e32 v2, v2, v36
	v_mul_f32_e32 v18, v18, v37
	v_mul_f32_e32 v3, v3, v38
	v_mul_f32_e32 v19, v19, v39
	v_mul_f32_e32 v0, v0, v64
	v_mul_f32_e32 v16, v16, v65
	v_mul_f32_e32 v1, v1, v66
	v_mul_f32_e32 v17, v17, v67
	v_mul_f32_e32 v2, v2, v68
	v_mul_f32_e32 v18, v18, v69
	v_mul_f32_e32 v3, v3, v70
	v_mul_f32_e32 v19, v19, v71
	v_cvt_pk_bf16_f32 v0, v0, v0
	v_cvt_pk_bf16_f32 v16, v16, v16
	v_cvt_pk_bf16_f32 v1, v1, v1
	v_cvt_pk_bf16_f32 v17, v17, v17
	v_cvt_pk_bf16_f32 v2, v2, v2
	v_cvt_pk_bf16_f32 v18, v18, v18
	v_cvt_pk_bf16_f32 v3, v3, v3
	v_cvt_pk_bf16_f32 v19, v19, v19
	s_add_u32 s8, s28, 0x0
	s_addc_u32 s9, s29, 0
	global_store_short v235, v0, s[8:9] offset:0
	global_store_short v235, v16, s[8:9] offset:64
	global_store_short v235, v1, s[8:9] offset:2048
	global_store_short v235, v17, s[8:9] offset:2112
	s_add_u32 s8, s28, 0x1000
	s_addc_u32 s9, s29, 0
	global_store_short v235, v2, s[8:9] offset:0
	global_store_short v235, v18, s[8:9] offset:64
	global_store_short v235, v3, s[8:9] offset:2048
	global_store_short v235, v19, s[8:9] offset:2112
	v_lshlrev_b32_e32 v40, 16, v132
	v_lshlrev_b32_e32 v41, 16, v133
	v_lshlrev_b32_e32 v42, 16, v134
	v_lshlrev_b32_e32 v43, 16, v135
	v_lshlrev_b32_e32 v44, 16, v136
	v_lshlrev_b32_e32 v45, 16, v137
	v_lshlrev_b32_e32 v46, 16, v138
	v_lshlrev_b32_e32 v47, 16, v139
	v_mul_f32_e32 v64, 0xbfb8aa3b, v40
	v_mul_f32_e32 v65, 0xbfb8aa3b, v41
	v_mul_f32_e32 v66, 0xbfb8aa3b, v42
	v_mul_f32_e32 v67, 0xbfb8aa3b, v43
	v_mul_f32_e32 v68, 0xbfb8aa3b, v44
	v_mul_f32_e32 v69, 0xbfb8aa3b, v45
	v_mul_f32_e32 v70, 0xbfb8aa3b, v46
	v_mul_f32_e32 v71, 0xbfb8aa3b, v47
	v_exp_f32_e32 v64, v64
	v_exp_f32_e32 v65, v65
	v_exp_f32_e32 v66, v66
	v_exp_f32_e32 v67, v67
	v_exp_f32_e32 v68, v68
	v_exp_f32_e32 v69, v69
	v_exp_f32_e32 v70, v70
	v_exp_f32_e32 v71, v71
	v_add_f32_e32 v64, 1.0, v64
	v_add_f32_e32 v65, 1.0, v65
	v_add_f32_e32 v66, 1.0, v66
	v_add_f32_e32 v67, 1.0, v67
	v_add_f32_e32 v68, 1.0, v68
	v_add_f32_e32 v69, 1.0, v69
	v_add_f32_e32 v70, 1.0, v70
	v_add_f32_e32 v71, 1.0, v71
	v_rcp_f32_e32 v64, v64
	v_rcp_f32_e32 v65, v65
	v_rcp_f32_e32 v66, v66
	v_rcp_f32_e32 v67, v67
	v_rcp_f32_e32 v68, v68
	v_rcp_f32_e32 v69, v69
	v_rcp_f32_e32 v70, v70
	v_rcp_f32_e32 v71, v71
	v_mul_f32_e32 v4, v4, v40
	v_mul_f32_e32 v20, v20, v41
	v_mul_f32_e32 v5, v5, v42
	v_mul_f32_e32 v21, v21, v43
	v_mul_f32_e32 v6, v6, v44
	v_mul_f32_e32 v22, v22, v45
	v_mul_f32_e32 v7, v7, v46
	v_mul_f32_e32 v23, v23, v47
	v_mul_f32_e32 v4, v4, v64
	v_mul_f32_e32 v20, v20, v65
	v_mul_f32_e32 v5, v5, v66
	v_mul_f32_e32 v21, v21, v67
	v_mul_f32_e32 v6, v6, v68
	v_mul_f32_e32 v22, v22, v69
; __device__ __forceinline__ float bf2f(bf16_t u) { return __uint_as_float(((unsigned)u) << 16); }
; __device__ __forceinline__ bf16_t f2bf(float f) { return (bf16_t)(cvtpk(f, 0.f) & 0xffffu); }
; __device__ __forceinline__ int crow(int r, int hi) { return (r & 3) + 8 * (r >> 2) + 4 * hi; }
; __device__ __forceinline__ float sigmoidf_(float x) { return __builtin_amdgcn_rcpf(1.f + __expf(-x)); }
; __device__ void phase_attn(const Params& p, char* lds) {
;     ...
;   for (int it = slot; it < nitems / 8; it += per) {
;     ...
; #pragma unroll
;     for (int r = 0; r < 16; ++r) {
;       const int orow = crow(r, hi);
; #pragma unroll
;       for (int d0 = 0; d0 < 2; ++d0) {
;         const float gt = bf2f(gin[2 * r + d0]);
;         Gw[(size_t)orow * 1024 + d0 * 32] = f2bf(o[d0][r] * rli[r] * gt * sigmoidf_(gt));
;       }
;     }
	v_mul_f32_e32 v7, v7, v70
	v_mul_f32_e32 v23, v23, v71
	v_cvt_pk_bf16_f32 v4, v4, v4
	v_cvt_pk_bf16_f32 v20, v20, v20
	v_cvt_pk_bf16_f32 v5, v5, v5
	v_cvt_pk_bf16_f32 v21, v21, v21
	v_cvt_pk_bf16_f32 v6, v6, v6
	v_cvt_pk_bf16_f32 v22, v22, v22
	v_cvt_pk_bf16_f32 v7, v7, v7
	v_cvt_pk_bf16_f32 v23, v23, v23
	s_add_u32 s8, s28, 0x4000
	s_addc_u32 s9, s29, 0
	global_store_short v235, v4, s[8:9] offset:0
	global_store_short v235, v20, s[8:9] offset:64
	global_store_short v235, v5, s[8:9] offset:2048
	global_store_short v235, v21, s[8:9] offset:2112
	s_add_u32 s8, s28, 0x5000
	s_addc_u32 s9, s29, 0
	global_store_short v235, v6, s[8:9] offset:0
	global_store_short v235, v22, s[8:9] offset:64
	global_store_short v235, v7, s[8:9] offset:2048
	global_store_short v235, v23, s[8:9] offset:2112
	v_lshlrev_b32_e32 v48, 16, v140
	v_lshlrev_b32_e32 v49, 16, v141
	v_lshlrev_b32_e32 v50, 16, v142
	v_lshlrev_b32_e32 v51, 16, v143
	v_lshlrev_b32_e32 v52, 16, v144
	v_lshlrev_b32_e32 v53, 16, v145
	v_lshlrev_b32_e32 v54, 16, v146
	v_lshlrev_b32_e32 v55, 16, v147
	v_mul_f32_e32 v64, 0xbfb8aa3b, v48
	v_mul_f32_e32 v65, 0xbfb8aa3b, v49
	v_mul_f32_e32 v66, 0xbfb8aa3b, v50
	v_mul_f32_e32 v67, 0xbfb8aa3b, v51
	v_mul_f32_e32 v68, 0xbfb8aa3b, v52
	v_mul_f32_e32 v69, 0xbfb8aa3b, v53
	v_mul_f32_e32 v70, 0xbfb8aa3b, v54
	v_mul_f32_e32 v71, 0xbfb8aa3b, v55
	v_exp_f32_e32 v64, v64
	v_exp_f32_e32 v65, v65
	v_exp_f32_e32 v66, v66
	v_exp_f32_e32 v67, v67
	v_exp_f32_e32 v68, v68
	v_exp_f32_e32 v69, v69
	v_exp_f32_e32 v70, v70
	v_exp_f32_e32 v71, v71
	v_add_f32_e32 v64, 1.0, v64
	v_add_f32_e32 v65, 1.0, v65
	v_add_f32_e32 v66, 1.0, v66
	v_add_f32_e32 v67, 1.0, v67
	v_add_f32_e32 v68, 1.0, v68
	v_add_f32_e32 v69, 1.0, v69
	v_add_f32_e32 v70, 1.0, v70
	v_add_f32_e32 v71, 1.0, v71
	v_rcp_f32_e32 v64, v64
	v_rcp_f32_e32 v65, v65
	v_rcp_f32_e32 v66, v66
	v_rcp_f32_e32 v67, v67
	v_rcp_f32_e32 v68, v68
	v_rcp_f32_e32 v69, v69
	v_rcp_f32_e32 v70, v70
	v_rcp_f32_e32 v71, v71
	v_mul_f32_e32 v8, v8, v48
	v_mul_f32_e32 v24, v24, v49
	v_mul_f32_e32 v9, v9, v50
	v_mul_f32_e32 v25, v25, v51
	v_mul_f32_e32 v10, v10, v52
	v_mul_f32_e32 v26, v26, v53
	v_mul_f32_e32 v11, v11, v54
	v_mul_f32_e32 v27, v27, v55
	v_mul_f32_e32 v8, v8, v64
	v_mul_f32_e32 v24, v24, v65
	v_mul_f32_e32 v9, v9, v66
	v_mul_f32_e32 v25, v25, v67
	v_mul_f32_e32 v10, v10, v68
	v_mul_f32_e32 v26, v26, v69
	v_mul_f32_e32 v11, v11, v70
	v_mul_f32_e32 v27, v27, v71
	v_cvt_pk_bf16_f32 v8, v8, v8
	v_cvt_pk_bf16_f32 v24, v24, v24
	v_cvt_pk_bf16_f32 v9, v9, v9
	v_cvt_pk_bf16_f32 v25, v25, v25
	v_cvt_pk_bf16_f32 v10, v10, v10
	v_cvt_pk_bf16_f32 v26, v26, v26
	v_cvt_pk_bf16_f32 v11, v11, v11
	v_cvt_pk_bf16_f32 v27, v27, v27
	s_add_u32 s8, s28, 0x8000
	s_addc_u32 s9, s29, 0
	global_store_short v235, v8, s[8:9] offset:0
	global_store_short v235, v24, s[8:9] offset:64
	global_store_short v235, v9, s[8:9] offset:2048
	global_store_short v235, v25, s[8:9] offset:2112
	s_add_u32 s8, s28, 0x9000
	s_addc_u32 s9, s29, 0
	global_store_short v235, v10, s[8:9] offset:0
	global_store_short v235, v26, s[8:9] offset:64
	global_store_short v235, v11, s[8:9] offset:2048
	global_store_short v235, v27, s[8:9] offset:2112
	v_lshlrev_b32_e32 v56, 16, v200
	v_lshlrev_b32_e32 v57, 16, v201
	v_lshlrev_b32_e32 v58, 16, v202
	v_lshlrev_b32_e32 v59, 16, v203
	v_lshlrev_b32_e32 v60, 16, v204
	v_lshlrev_b32_e32 v61, 16, v205
	v_lshlrev_b32_e32 v62, 16, v206
	v_lshlrev_b32_e32 v63, 16, v207
	v_mul_f32_e32 v64, 0xbfb8aa3b, v56
	v_mul_f32_e32 v65, 0xbfb8aa3b, v57
	v_mul_f32_e32 v66, 0xbfb8aa3b, v58
	v_mul_f32_e32 v67, 0xbfb8aa3b, v59
	v_mul_f32_e32 v68, 0xbfb8aa3b, v60
	v_mul_f32_e32 v69, 0xbfb8aa3b, v61
	v_mul_f32_e32 v70, 0xbfb8aa3b, v62
	v_mul_f32_e32 v71, 0xbfb8aa3b, v63
	v_exp_f32_e32 v64, v64
	v_exp_f32_e32 v65, v65
	v_exp_f32_e32 v66, v66
	v_exp_f32_e32 v67, v67
	v_exp_f32_e32 v68, v68
	v_exp_f32_e32 v69, v69
	v_exp_f32_e32 v70, v70
	v_exp_f32_e32 v71, v71
	v_add_f32_e32 v64, 1.0, v64
	v_add_f32_e32 v65, 1.0, v65
	v_add_f32_e32 v66, 1.0, v66
	v_add_f32_e32 v67, 1.0, v67
	v_add_f32_e32 v68, 1.0, v68
	v_add_f32_e32 v69, 1.0, v69
	v_add_f32_e32 v70, 1.0, v70
	v_add_f32_e32 v71, 1.0, v71
	v_rcp_f32_e32 v64, v64
	v_rcp_f32_e32 v65, v65
	v_rcp_f32_e32 v66, v66
	v_rcp_f32_e32 v67, v67
	v_rcp_f32_e32 v68, v68
	v_rcp_f32_e32 v69, v69
	v_rcp_f32_e32 v70, v70
	v_rcp_f32_e32 v71, v71
	v_mul_f32_e32 v12, v12, v56
	v_mul_f32_e32 v28, v28, v57
	v_mul_f32_e32 v13, v13, v58
	v_mul_f32_e32 v29, v29, v59
	v_mul_f32_e32 v14, v14, v60
	v_mul_f32_e32 v30, v30, v61
	v_mul_f32_e32 v15, v15, v62
	v_mul_f32_e32 v31, v31, v63
	v_mul_f32_e32 v12, v12, v64
	v_mul_f32_e32 v28, v28, v65
	v_mul_f32_e32 v13, v13, v66
	v_mul_f32_e32 v29, v29, v67
	v_mul_f32_e32 v14, v14, v68
	v_mul_f32_e32 v30, v30, v69
	v_mul_f32_e32 v15, v15, v70
	v_mul_f32_e32 v31, v31, v71
	v_cvt_pk_bf16_f32 v12, v12, v12
	v_cvt_pk_bf16_f32 v28, v28, v28
	v_cvt_pk_bf16_f32 v13, v13, v13
	v_cvt_pk_bf16_f32 v29, v29, v29
	v_cvt_pk_bf16_f32 v14, v14, v14
	v_cvt_pk_bf16_f32 v30, v30, v30
	v_cvt_pk_bf16_f32 v15, v15, v15
	v_cvt_pk_bf16_f32 v31, v31, v31
	s_add_u32 s8, s28, 0xc000
	s_addc_u32 s9, s29, 0
	global_store_short v235, v12, s[8:9] offset:0
	global_store_short v235, v28, s[8:9] offset:64
	global_store_short v235, v13, s[8:9] offset:2048
	global_store_short v235, v29, s[8:9] offset:2112
	s_add_u32 s8, s28, 0xd000
	s_addc_u32 s9, s29, 0
	global_store_short v235, v14, s[8:9] offset:0
	global_store_short v235, v30, s[8:9] offset:64
	global_store_short v235, v15, s[8:9] offset:2048
	global_store_short v235, v31, s[8:9] offset:2112
	s_add_i32 s12, s12, s33
	s_cmpk_lt_u32 s12, 0x200
	s_cbranch_scc1 .Lat_item
	s_branch .Lat_done
